# ATT2F: ALiBi bias init with plain v_add_f32 instead of v_pk_add_f32; second score block's init deferred into the first QK MFMA gaps
# speedup vs baseline: 1.0500x; 1.0006x over previous
; #define MFMA32(a, b, c) __builtin_amdgcn_mfma_f32_32x32x16_bf16((a), (b), (c), 0, 0, 0)
; template <bool DIFF, bool FIXED, bool F32SRC> ...
;     ...
;                 if (j < cq) {
;                     const float base = -slopeL2 * dq - mrun;
; #pragma unroll
;                     for (int r = 0; r < 16; ++r) { const float c = (float)((r & 3) + 8 * (r >> 2)); a0[r] = slopeL2 * c + base; a1[r] = slopeL2 * (c + 32.f) + base; }
;     ...
;             for (int ks = 0; ks < 2; ++ks) { a0 = MFMA32(kf0[ks], qf[ks], a0); a1 = MFMA32(kf1[ks], qf[ks], a1); }
.LBB0_419:
	s_andn2_b64 vcc, exec, s[18:19]
	s_cbranch_vccnz .LBB0_421
	v_fma_f32 v0, -v135, v0, -v132
	v_add_f32_e32 v80, v174, v0
	v_add_f32_e32 v81, v175, v0
	v_add_f32_e32 v78, v172, v0
	v_add_f32_e32 v79, v173, v0
	v_add_f32_e32 v76, v170, v0
	v_add_f32_e32 v77, v171, v0
	v_add_f32_e32 v74, v168, v0
	v_add_f32_e32 v75, v169, v0
	v_add_f32_e32 v72, v166, v0
	v_add_f32_e32 v73, v167, v0
	v_add_f32_e32 v70, v164, v0
	v_add_f32_e32 v71, v165, v0
	v_add_f32_e32 v68, v162, v0
	v_add_f32_e32 v69, v163, v0
	v_add_f32_e32 v66, v134, v0
	v_add_f32_e32 v67, v135, v0
	s_waitcnt lgkmcnt(4)
	v_add_f32_e32 v96, v178, v0
	v_mfma_f32_32x32x16_bf16 v[66:81], v[114:117], v[98:101], v[66:81]
	v_add_f32_e32 v97, v179, v0
	v_add_f32_e32 v94, v180, v0
	v_add_f32_e32 v95, v181, v0
	v_add_f32_e32 v92, v182, v0
	v_add_f32_e32 v93, v183, v0
	v_mfma_f32_32x32x16_bf16 v[66:81], v[118:121], v[102:105], v[66:81]
	v_add_f32_e32 v90, v184, v0
	v_add_f32_e32 v91, v185, v0
	v_add_f32_e32 v88, v186, v0
	v_add_f32_e32 v89, v187, v0
	v_add_f32_e32 v86, v188, v0
	v_mfma_f32_32x32x16_bf16 v[66:81], v[122:125], v[106:109], v[66:81]
	v_add_f32_e32 v87, v189, v0
	v_add_f32_e32 v84, v190, v0
	v_add_f32_e32 v85, v191, v0
	v_add_f32_e32 v82, v192, v0
	v_add_f32_e32 v83, v193, v0
	v_mfma_f32_32x32x16_bf16 v[66:81], v[126:129], v[110:113], v[66:81]
	s_branch .Lqk4_done

; #define LAS __attribute__((address_space(3)))
; template <bool DIFF, bool FIXED, bool F32SRC> ...
;     ...
;             for (int ks = 0; ks < 2; ++ks) { a0 = MFMA32(kf0[ks], qf[ks], a0); a1 = MFMA32(kf1[ks], qf[ks], a1); }
;             __builtin_amdgcn_sched_barrier(0);
; #pragma unroll
;             for (int ks = 0; ks < 2; ++ks) { kf0[ks] = *(const LAS bf16x8*)(kb + koff[ks + 2]); kf1[ks] = *(const LAS bf16x8*)(kb + koff[ks + 2] + 32 * RB); }
;             __builtin_amdgcn_sched_barrier(0);
; #pragma unroll
;             for (int ks = 0; ks < 2; ++ks) { a0 = MFMA32(kf0[ks], qf[ks + 2], a0); a1 = MFMA32(kf1[ks], qf[ks + 2], a1); }
;             __builtin_amdgcn_sched_barrier(0);
;             bf16x8 vf[4];
;     ...
;             if (!FIXED) {
;             float mx = fmaxf(fmaxf(a0[0], a1[0]), fmaxf(a0[1], a1[1]));
; #pragma unroll
;             for (int r = 2; r < 16; r += 2) mx = fmaxf(fmaxf(mx, fmaxf(a0[r], a1[r])), fmaxf(a0[r + 1], a1[r + 1]));
;             mx = x32_max(mx);
;             if (__any(mx > 0.f)) {
;                 const float dl = fmaxf(mx, 0.f), al = __builtin_amdgcn_exp2f(-dl);
;                 lrun *= al; mrun += dl;
; #pragma unroll
;                 for (int r = 0; r < 16; ++r) { a0[r] -= dl; a1[r] -= dl; }
; #pragma unroll
;                 for (int db = 0; db < NDB; ++db)
; #pragma unroll
;                     for (int r = 0; r < 16; ++r) o[db][r] *= al;
;             }
;             }
;             float ls = 0.f;
; #pragma unroll
;             for (int r = 0; r < 16; ++r) { a0[r] = __builtin_amdgcn_exp2f(a0[r]); a1[r] = __builtin_amdgcn_exp2f(a1[r]); ls += a0[r] + a1[r]; }
;             lrun += ls;
;             bf16x8 pf[4];
; #pragma unroll
;             for (int ks = 0; ks < 4; ++ks) { u32x4 p;
; #pragma unroll
;                 for (int e = 0; e < 4; ++e) p[e] = (ks < 2) ? cvt_pk_bf16(a0[8 * ks + 2 * e], a0[8 * ks + 2 * e + 1]) : cvt_pk_bf16(a1[8 * (ks - 2) + 2 * e], a1[8 * (ks - 2) + 2 * e + 1]);
;                 pf[ks] = __builtin_bit_cast(bf16x8, p); }
; #pragma unroll
;             for (int db = 0; db < NDB; ++db) {
;                 ATT_VLOAD(vf, db);
;                 __builtin_amdgcn_sched_barrier(0);
; #pragma unroll
;                 for (int ks = 0; ks < 4; ++ks) o[db] = MFMA32(vf[ks], pf[ks], o[db]);
;                 __builtin_amdgcn_sched_barrier(0);
;             }
.Lqk4_done:
	v_add_u32_e32 v0, s66, v225
	ds_read_b64_tr_b16 v[114:115], v0 offset:16384
	ds_read_b64_tr_b16 v[116:117], v0 offset:18432
	ds_read_b64_tr_b16 v[118:119], v0 offset:16896
	ds_read_b64_tr_b16 v[120:121], v0 offset:18944
	ds_read_b64_tr_b16 v[122:123], v0 offset:17408
	ds_read_b64_tr_b16 v[124:125], v0 offset:19456
	ds_read_b64_tr_b16 v[126:127], v0 offset:17920
	ds_read_b64_tr_b16 v[128:129], v0 offset:19968
	s_waitcnt lgkmcnt(8)
	v_mfma_f32_32x32x16_bf16 v[82:97], v[146:149], v[98:101], v[82:97]
	s_nop 1
	v_exp_f32_e32 v66, v66
	v_exp_f32_e32 v67, v67
	v_exp_f32_e32 v68, v68
	v_mfma_f32_32x32x16_bf16 v[82:97], v[150:153], v[102:105], v[82:97]
	v_exp_f32_e32 v69, v69
	v_exp_f32_e32 v70, v70
	v_exp_f32_e32 v71, v71
	v_mfma_f32_32x32x16_bf16 v[82:97], v[154:157], v[106:109], v[82:97]
	v_exp_f32_e32 v72, v72
	v_exp_f32_e32 v73, v73
	v_add_f32_e32 v228, v66, v67
	v_add_f32_e32 v229, v68, v69
	v_cvt_pk_bf16_f32 v66, v66, v67
	v_mfma_f32_32x32x16_bf16 v[82:97], v[158:161], v[110:113], v[82:97]
	v_add_f32_e32 v228, v228, v70
	v_add_f32_e32 v229, v229, v71
	v_cvt_pk_bf16_f32 v67, v68, v69
	v_add_f32_e32 v228, v228, v72
	v_add_f32_e32 v229, v229, v73
	v_cvt_pk_bf16_f32 v68, v70, v71
	v_cvt_pk_bf16_f32 v69, v72, v73
	s_waitcnt lgkmcnt(7)
	ds_read_b64_tr_b16 v[146:147], v0 offset:20480
	ds_read_b64_tr_b16 v[148:149], v0 offset:22528
	ds_read_b64_tr_b16 v[150:151], v0 offset:20992
	ds_read_b64_tr_b16 v[152:153], v0 offset:23040
	ds_read_b64_tr_b16 v[154:155], v0 offset:21504
	ds_read_b64_tr_b16 v[156:157], v0 offset:23552
	ds_read_b64_tr_b16 v[158:159], v0 offset:22016
	ds_read_b64_tr_b16 v[160:161], v0 offset:24064
	s_waitcnt lgkmcnt(8)
	v_mfma_f32_32x32x16_bf16 v[50:65], v[114:117], v[66:69], v[50:65]
	v_exp_f32_e32 v74, v74
	v_exp_f32_e32 v75, v75
	v_exp_f32_e32 v76, v76
	v_mfma_f32_32x32x16_bf16 v[34:49], v[118:121], v[66:69], v[34:49]
	v_exp_f32_e32 v77, v77
	v_exp_f32_e32 v78, v78
	v_add_f32_e32 v228, v228, v74
	v_add_f32_e32 v229, v229, v75
	v_cvt_pk_bf16_f32 v70, v74, v75
	v_mfma_f32_32x32x16_bf16 v[18:33], v[122:125], v[66:69], v[18:33]
	v_exp_f32_e32 v79, v79
	v_exp_f32_e32 v80, v80
	v_add_f32_e32 v228, v228, v76
	v_add_f32_e32 v229, v229, v77
	v_cvt_pk_bf16_f32 v71, v76, v77
	v_mfma_f32_32x32x16_bf16 v[2:17], v[126:129], v[66:69], v[2:17]
	v_exp_f32_e32 v81, v81
	v_add_f32_e32 v228, v228, v78
	v_add_f32_e32 v229, v229, v79
	v_cvt_pk_bf16_f32 v72, v78, v79
	v_add_f32_e32 v228, v228, v80
	v_add_f32_e32 v229, v229, v81
	v_cvt_pk_bf16_f32 v73, v80, v81
	s_waitcnt lgkmcnt(7)
	ds_read_b64_tr_b16 v[114:115], v0 offset:24576
	ds_read_b64_tr_b16 v[116:117], v0 offset:26624
	ds_read_b64_tr_b16 v[118:119], v0 offset:25088
	ds_read_b64_tr_b16 v[120:121], v0 offset:27136
	ds_read_b64_tr_b16 v[122:123], v0 offset:25600
	ds_read_b64_tr_b16 v[124:125], v0 offset:27648
	ds_read_b64_tr_b16 v[126:127], v0 offset:26112
	ds_read_b64_tr_b16 v[128:129], v0 offset:28160
	s_waitcnt lgkmcnt(8)
	v_mfma_f32_32x32x16_bf16 v[50:65], v[146:149], v[70:73], v[50:65]
	v_exp_f32_e32 v82, v82
	v_exp_f32_e32 v83, v83
	v_exp_f32_e32 v84, v84
	v_mfma_f32_32x32x16_bf16 v[34:49], v[150:153], v[70:73], v[34:49]
	v_exp_f32_e32 v85, v85
	v_exp_f32_e32 v86, v86
	v_add_f32_e32 v228, v228, v82
	v_add_f32_e32 v229, v229, v83
	v_cvt_pk_bf16_f32 v74, v82, v83
	v_mfma_f32_32x32x16_bf16 v[18:33], v[154:157], v[70:73], v[18:33]
	v_exp_f32_e32 v87, v87
	v_exp_f32_e32 v88, v88
	v_add_f32_e32 v228, v228, v84
	v_add_f32_e32 v229, v229, v85
	v_cvt_pk_bf16_f32 v75, v84, v85
	v_mfma_f32_32x32x16_bf16 v[2:17], v[158:161], v[70:73], v[2:17]
	v_exp_f32_e32 v89, v89
	v_add_f32_e32 v228, v228, v86
	v_add_f32_e32 v229, v229, v87
	v_cvt_pk_bf16_f32 v76, v86, v87
	v_add_f32_e32 v228, v228, v88
	v_add_f32_e32 v229, v229, v89
	v_cvt_pk_bf16_f32 v77, v88, v89
	s_waitcnt lgkmcnt(7)
	ds_read_b64_tr_b16 v[146:147], v0 offset:28672
	ds_read_b64_tr_b16 v[148:149], v0 offset:30720
	ds_read_b64_tr_b16 v[150:151], v0 offset:29184
	ds_read_b64_tr_b16 v[152:153], v0 offset:31232
	ds_read_b64_tr_b16 v[154:155], v0 offset:29696
	ds_read_b64_tr_b16 v[156:157], v0 offset:31744
	ds_read_b64_tr_b16 v[158:159], v0 offset:30208
	ds_read_b64_tr_b16 v[160:161], v0 offset:32256
	s_waitcnt lgkmcnt(8)
	v_mfma_f32_32x32x16_bf16 v[50:65], v[114:117], v[74:77], v[50:65]
	v_exp_f32_e32 v90, v90
	v_exp_f32_e32 v91, v91
	v_exp_f32_e32 v92, v92
	v_mfma_f32_32x32x16_bf16 v[34:49], v[118:121], v[74:77], v[34:49]
	v_exp_f32_e32 v93, v93
	v_exp_f32_e32 v94, v94
	v_add_f32_e32 v228, v228, v90
	v_add_f32_e32 v229, v229, v91
	v_cvt_pk_bf16_f32 v78, v90, v91
	v_mfma_f32_32x32x16_bf16 v[18:33], v[122:125], v[74:77], v[18:33]
	v_exp_f32_e32 v95, v95
	v_exp_f32_e32 v96, v96
	v_add_f32_e32 v228, v228, v92
	v_add_f32_e32 v229, v229, v93
	v_cvt_pk_bf16_f32 v79, v92, v93
	v_mfma_f32_32x32x16_bf16 v[2:17], v[126:129], v[74:77], v[2:17]
	v_exp_f32_e32 v97, v97
	v_add_f32_e32 v228, v228, v94
	v_add_f32_e32 v229, v229, v95
	v_cvt_pk_bf16_f32 v80, v94, v95
	v_add_f32_e32 v228, v228, v96
	v_add_f32_e32 v229, v229, v97
	v_cvt_pk_bf16_f32 v81, v96, v97
	s_waitcnt lgkmcnt(0)
	v_add_f32_e32 v228, v228, v229
	s_andn2_b64 vcc, exec, s[16:17]
	s_cbranch_vccnz .Lpv3_nodma
	v_mfma_f32_32x32x16_bf16 v[50:65], v[146:149], v[78:81], v[50:65]
	v_add_f32_e32 v219, v219, v228
	s_ashr_i32 s13, s12, 31
	s_lshl_b64 s[18:19], s[12:13], 11
	s_add_u32 s66, s50, s18
	s_addc_u32 s67, s60, s19
	s_add_u32 s18, s63, s18
	s_addc_u32 s19, s64, s19
	s_lshl_b32 s13, s28, 15
	s_addk_i32 s13, 0x8000
	s_cmp_gt_i32 s28, 0
	s_cselect_b32 s13, s13, 0x10000
	s_add_i32 s13, s51, s13
	v_lshl_add_u64 v[230:231], v[136:137], 1, s[66:67]
	s_mov_b32 m0, s13
	s_nop 0
	global_load_lds_dwordx4 v[230:231], off
	v_mfma_f32_32x32x16_bf16 v[34:49], v[150:153], v[78:81], v[34:49]
	v_lshl_add_u64 v[230:231], v[138:139], 1, s[18:19]
	s_add_i32 m0, s13, 0x4000
	s_nop 0
	global_load_lds_dwordx4 v[230:231], off
	v_mfma_f32_32x32x16_bf16 v[18:33], v[154:157], v[78:81], v[18:33]
	v_lshl_add_u64 v[230:231], v[140:141], 1, s[66:67]
	s_add_i32 m0, s13, 0x400
	s_nop 0
	global_load_lds_dwordx4 v[230:231], off
	v_mfma_f32_32x32x16_bf16 v[2:17], v[158:161], v[78:81], v[2:17]
	v_lshl_add_u64 v[230:231], v[142:143], 1, s[18:19]
	s_add_i32 m0, s13, 0x4400
	s_nop 0
	global_load_lds_dwordx4 v[230:231], off
	s_add_i32 s13, s25, 2
	s_branch .Lpv3_done
